# strategy: LDS bank conflicts - attention K tile chunk swizzle keyed on row&15 instead of row&7 so each 16-lane ds_read_b128 group hits 64 distinct banks
# speedup vs baseline: 1.0156x; 1.0156x over previous
; #define SBAR() __builtin_amdgcn_sched_barrier(0)
; __device__ __forceinline__ int v_st(int k, int c) { const int kk = (k & ~0xC) | ((k & 4) << 1) | ((k & 8) >> 1); return ((kk >> 3) * 4 + (c >> 5)) * 512 + ((kk & 7) * 32 + (c & 31)) * 2; }
; __device__ __forceinline__ int v_rd_base(int lane) { return ((lane & 3) << 3) | (((lane >> 2) & 3) << 6) | (((lane >> 4) & 1) << 5) | (((lane >> 5) & 1) << 8); }
; #define VMW() asm volatile("s_waitcnt vmcnt(0)" ::: "memory")
; #define SLOAD_H(Kp, Vp, k0) do { S.st_v0 = load8h(ROW(Vp, k0, sr)); S.st_v1 = load8h(ROW(Vp, k0, 32 + sr));              \
;                          S.st_k0 = load8h(ROW(Kp, k0, sr)); S.st_k1 = load8h(ROW(Kp, k0, 32 + sr)); } while (0)
; __device__ __forceinline__ void block(const BlockRef& cur, const BlockRef& nxt, char* lds, Seam& S) {
;     ...
;     { const float cref = cur.C[cur.P0]; const int n4 = (cur.P0 + QB) >> 2; int tl = threadIdx.x; asm volatile("" : "+v"(tl));
;       for (int i = tl; i < n4; i += 512) { const f32x4 c4 = *(const f32x4*)(cur.C + 4 * i); *(f32x4*)(bias + 4 * i) = (cref - c4) * INV_SCALE; } }
;     __syncthreads();
;     int* jl = (int*)(lds + LDS_BIAS - 16);
;     if (wid == 0) { const float lim = -(88.0f + 2.0f * cur.nrm) * INV_SCALE; const int t1 = lane + 64;
;         const bool d0 = lane < NTC && bias[64 * lane + 63] < lim, d1 = t1 < NTC && bias[64 * t1 + 63] < lim;
;         int cnt = __popcll(__ballot(d0)) + __popcll(__ballot(d1)); cnt &= ~1; if (cnt > NTC - 4) cnt = NTC - 4;
;         if (lane == 0) *jl = cnt; }
;     __syncthreads();
;     const int j_lo = __builtin_amdgcn_readfirstlane(*jl), NT = NTC - j_lo;
;     const lds_cf bt0 = (lds_cf)(__attribute__((address_space(3))) char*)lds + LDS_BIAS / 4 + 4 * hi;
;     float m_reg = -1e30f, l_reg = 0; f32x16 o[4] = {};
;     const int sr = tid >> 4, sc = (tid & 15) * 8, vst0 = v_st(sr, sc), vst1 = v_st(32 + sr, sc), kws = KSWZ(sr, sc * 2);
;     const int vb0 = (int)(uintptr_t)V_lds + v_rd_base(lane);
;     const bf16_t* Kh = cur.K; const bf16_t* Vh = cur.Vp();
;     ...
;     f32x16 pA0, pA1, pB0, pB1; float mnA, mnB, alA, alB; bf16x8 pa0, pa1, pa2, pa3;
;     SLOAD_H(Kh, Vh, KBASE(0)); VMW(); SWRITE_HK(0); __syncthreads();
;     SWRITE_HV(0); SBAR();
;     if (NT > 1) { SLOAD_H(Kh, Vh, KBASE(1)); }
.LBB0_1133:
	v_mov_b32_e32 v0, s64
	s_waitcnt lgkmcnt(0)
	s_barrier
	ds_read_b32 v0, v0
	v_lshlrev_b32_e32 v1, 3, v174
	v_ashrrev_i32_e32 v187, 4, v174
	s_waitcnt lgkmcnt(0)
	v_readfirstlane_b32 s68, v0
	s_sub_i32 s65, s58, s68
	s_add_u32 s8, s18, 0x4100000
	v_and_b32_e32 v0, 0x78, v1
	s_addc_u32 s9, s19, 0
	s_lshl_b32 s67, s68, 6
	v_lshlrev_b32_e32 v160, 1, v0
	v_add_u32_e32 v0, 32, v187
	s_waitcnt vmcnt(0)
	v_add_u32_e32 v2, s67, v187
	v_ashrrev_i32_e32 v3, 31, v2
	v_add_u32_e32 v6, s67, v0
	v_lshlrev_b64 v[2:3], 8, v[2:3]
	v_ashrrev_i32_e32 v7, 31, v6
	v_lshl_add_u64 v[4:5], s[8:9], 0, v[2:3]
	v_lshlrev_b64 v[6:7], 8, v[6:7]
	v_lshl_add_u64 v[2:3], s[18:19], 0, v[2:3]
	v_lshl_add_u64 v[2:3], v[2:3], 0, v[160:161]
	v_lshl_add_u64 v[8:9], s[18:19], 0, v[6:7]
	v_lshl_add_u64 v[8:9], v[8:9], 0, v[160:161]
	global_load_dwordx4 v[36:39], v[2:3], off
	global_load_dwordx4 v[44:47], v[8:9], off
	v_lshl_add_u64 v[2:3], v[4:5], 0, v[160:161]
	v_lshl_add_u64 v[4:5], s[8:9], 0, v[6:7]
	v_lshl_add_u64 v[4:5], v[4:5], 0, v[160:161]
	global_load_dwordx4 v[32:35], v[2:3], off
	global_load_dwordx4 v[40:43], v[4:5], off
	v_and_b32_e32 v3, 0xfffff0, v187
	v_lshlrev_b32_e32 v4, 1, v187
	v_lshrrev_b32_e32 v5, 1, v187
	v_and_b32_e32 v6, 3, v187
	v_and_or_b32 v3, v4, 8, v3
	v_and_or_b32 v4, v5, 4, v6
	v_and_b32_e32 v5, 0xfffff0, v0
	v_lshlrev_b32_e32 v6, 1, v0
	v_and_or_b32 v5, v6, 8, v5
	v_and_b32_e32 v2, 0xf0, v174
	v_bfe_u32 v1, v1, 5, 2
	v_lshlrev_b32_e32 v7, 8, v187
	v_lshrrev_b32_e32 v3, 1, v3
	v_lshrrev_b32_e32 v5, 1, v5
	v_bitop3_b32 v2, v160, v7, v2 bitop3:0xde
	v_or_b32_e32 v3, v3, v1
	v_or_b32_e32 v1, v5, v1
	v_lshlrev_b32_e32 v4, 6, v4
	v_and_b32_e32 v8, 48, v160
	v_add_u32_e32 v188, 0, v2
	v_lshlrev_b32_e32 v2, 9, v3
	v_lshlrev_b32_e32 v1, 9, v1
	s_waitcnt vmcnt(0)
	v_or3_b32 v2, v2, v4, v8
	v_or3_b32 v1, v1, v4, v8
	v_add_u32_e32 v189, 0, v2
	v_add_u32_e32 v190, 0, v1
	s_waitcnt vmcnt(3)
	ds_write_b128 v188, v[36:39] offset:32768
	s_waitcnt vmcnt(2)
	ds_write_b128 v188, v[44:47] offset:40960
	s_waitcnt lgkmcnt(0)
	s_barrier
	s_waitcnt vmcnt(1)
	ds_write_b128 v189, v[32:35]
	s_waitcnt vmcnt(0)
	ds_write_b128 v190, v[40:43]
	s_cmp_gt_i32 s65, 1
	s_cselect_b64 s[58:59], -1, 0
	s_cmp_lt_i32 s65, 2
	s_cbranch_scc1 .LBB0_1135
	s_add_i32 s6, s67, 64
	v_add_u32_e32 v2, s6, v187
	v_ashrrev_i32_e32 v3, 31, v2
	v_add_u32_e32 v0, s6, v0
	v_lshlrev_b64 v[2:3], 8, v[2:3]
	v_ashrrev_i32_e32 v1, 31, v0
	v_lshl_add_u64 v[4:5], s[8:9], 0, v[2:3]
	v_lshlrev_b64 v[0:1], 8, v[0:1]
	v_lshl_add_u64 v[2:3], s[18:19], 0, v[2:3]
	v_lshl_add_u64 v[4:5], v[4:5], 0, v[160:161]
	v_lshl_add_u64 v[6:7], s[8:9], 0, v[0:1]
	v_lshl_add_u64 v[2:3], v[2:3], 0, v[160:161]
	v_lshl_add_u64 v[0:1], s[18:19], 0, v[0:1]
	v_lshl_add_u64 v[6:7], v[6:7], 0, v[160:161]
	global_load_dwordx4 v[32:35], v[4:5], off
	global_load_dwordx4 v[40:43], v[6:7], off
	v_lshl_add_u64 v[0:1], v[0:1], 0, v[160:161]
	global_load_dwordx4 v[36:39], v[2:3], off
	global_load_dwordx4 v[44:47], v[0:1], off
; __device__ __forceinline__ void mask_tile(f32x16& p0, f32x16& p1, int dq, unsigned W) {
;     const float NEG = -__builtin_inff();
; #pragma unroll
;     for (int r = 0; r < 16; ++r) { const int c = (r & 3) + 8 * (r >> 2);
;         if ((unsigned)(dq - c) >= W) p0[r] = NEG;
;         if ((unsigned)(dq - c - 32) >= W) p1[r] = NEG; }
; }
; __device__ __forceinline__ void bias_init(f32x16& p0, f32x16& p1, lds_cf bt) {
; #pragma unroll
;     for (int g = 0; g < 4; ++g) { const f32x4 a = *(const __attribute__((address_space(3))) f32x4*)(bt + 8 * g), b = *(const __attribute__((address_space(3))) f32x4*)(bt + 32 + 8 * g);
;         p0[4 * g] = a[0]; p0[4 * g + 1] = a[1]; p0[4 * g + 2] = a[2]; p0[4 * g + 3] = a[3];
;         p1[4 * g] = b[0]; p1[4 * g + 1] = b[1]; p1[4 * g + 2] = b[2]; p1[4 * g + 3] = b[3]; }
; }
; template <int KB>
; __device__ __forceinline__ void qkt(f32x16& p0, f32x16& p1, const char* K_lds, int r32, int hi, const bf16x8* qr, lds_cf bt) {
;     bias_init(p0, p1, bt);
;     const char* kb[4];
; #pragma unroll
;     for (int dd = 0; dd < 4; ++dd) kb[dd] = K_lds + KB * SHM_K + KSWZ(r32, (dd * 16 + hi * 8) * 2);
; #pragma unroll
;     for (int d0 = 0; d0 < 8; ++d0) { const char* a = kb[d0 & 3] + (d0 >> 2) * 128;
;         bf16x8 b0 = *reinterpret_cast<const bf16x8*>(a);
;         bf16x8 b1 = *reinterpret_cast<const bf16x8*>(a + 32 * 256);
;         p0 = __builtin_amdgcn_mfma_f32_32x32x16_bf16(b0, qr[d0], p0, 0, 0, 0);
;         p1 = __builtin_amdgcn_mfma_f32_32x32x16_bf16(b1, qr[d0], p1, 0, 0, 0); }
; }
.LBB0_1135:
	v_lshrrev_b32_e32 v176, 5, v175
	s_ashr_i32 s6, s66, 1
	v_lshlrev_b32_e32 v48, 2, v176
	v_and_b32_e32 v177, 31, v174
	s_and_b32 s44, s6, 0xffffffe0
	v_lshlrev_b32_e32 v162, 4, v176
	s_add_i32 s45, s44, s56
	v_sub_u32_e32 v0, v177, v48
	v_add_u32_e32 v183, s63, v162
	v_add_u32_e32 v181, s45, v0
	v_lshlrev_b32_e32 v0, 4, v174
	v_and_b32_e32 v74, 0xf0, v0
	v_lshlrev_b32_e32 v49, 8, v177
	v_xad_u32 v0, v162, v74, 0
	v_add_u32_e32 v163, v0, v49
	v_xor_b32_e32 v252, 0x80, v163
	v_lshl_add_u32 v12, s67, 2, v183
	ds_read_b128 v[0:3], v163 offset:32768
	ds_read_b128 v[16:19], v12
	ds_read_b128 v[20:23], v12 offset:32
	ds_read_b128 v[24:27], v12 offset:64
	ds_read_b128 v[28:31], v12 offset:96
	ds_read_b128 v[50:53], v163 offset:40960
	ds_read_b128 v[54:57], v252 offset:32768
	s_waitcnt lgkmcnt(2)
	v_mfma_f32_32x32x16_bf16 v[16:31], v[0:3], v[112:115], v[16:31]
	ds_read_b128 v[0:3], v12 offset:128
	ds_read_b128 v[4:7], v12 offset:160
	ds_read_b128 v[8:11], v12 offset:192
	ds_read_b128 v[12:15], v12 offset:224
	v_or_b32_e32 v58, 32, v162
	v_xad_u32 v58, v58, v74, 0
	v_add_u32_e32 v184, v58, v49
	v_xor_b32_e32 v253, 0x80, v184
	ds_read_b128 v[58:61], v252 offset:40960
	v_or_b32_e32 v66, 64, v162
	v_xad_u32 v66, v66, v74, 0
	s_waitcnt lgkmcnt(1)
	v_mfma_f32_32x32x16_bf16 v[0:15], v[50:53], v[112:115], v[0:15]
	ds_read_b128 v[50:53], v184 offset:32768
	ds_read_b128 v[62:65], v253 offset:32768
	v_add_u32_e32 v185, v66, v49
	v_xor_b32_e32 v254, 0x80, v185
	ds_read_b128 v[66:69], v253 offset:40960
	v_or_b32_e32 v75, 0x60, v162
	v_xad_u32 v74, v75, v74, 0
	v_add_u32_e32 v186, v74, v49
	v_xor_b32_e32 v255, 0x80, v186
	s_or_b32 s6, s67, 63
	s_waitcnt lgkmcnt(2)
	v_mfma_f32_32x32x16_bf16 v[16:31], v[50:53], v[116:119], v[16:31]
	ds_read_b128 v[50:53], v184 offset:40960
	s_cmp_le_i32 s6, s45
	s_waitcnt lgkmcnt(0)
	v_mfma_f32_32x32x16_bf16 v[0:15], v[50:53], v[116:119], v[0:15]
	ds_read_b128 v[50:53], v185 offset:32768
	ds_read_b128 v[70:73], v254 offset:32768
	ds_read_b128 v[74:77], v254 offset:40960
	s_waitcnt lgkmcnt(2)
	v_mfma_f32_32x32x16_bf16 v[16:31], v[50:53], v[120:123], v[16:31]
	ds_read_b128 v[50:53], v185 offset:40960
	s_waitcnt lgkmcnt(0)
	v_mfma_f32_32x32x16_bf16 v[0:15], v[50:53], v[120:123], v[0:15]
	ds_read_b128 v[50:53], v186 offset:32768
	ds_read_b128 v[78:81], v255 offset:32768
	s_waitcnt lgkmcnt(1)
	v_mfma_f32_32x32x16_bf16 v[16:31], v[50:53], v[124:127], v[16:31]
	ds_read_b128 v[50:53], v186 offset:40960
	ds_read_b128 v[82:85], v255 offset:40960
	s_waitcnt lgkmcnt(1)
	v_mfma_f32_32x32x16_bf16 v[0:15], v[50:53], v[124:127], v[0:15]
	v_mfma_f32_32x32x16_bf16 v[16:31], v[54:57], v[108:111], v[16:31]
	v_mfma_f32_32x32x16_bf16 v[0:15], v[58:61], v[108:111], v[0:15]
	v_mfma_f32_32x32x16_bf16 v[16:31], v[62:65], v[104:107], v[16:31]
	v_mfma_f32_32x32x16_bf16 v[0:15], v[66:69], v[104:107], v[0:15]
	v_mfma_f32_32x32x16_bf16 v[16:31], v[70:73], v[100:103], v[16:31]
	v_mfma_f32_32x32x16_bf16 v[0:15], v[74:77], v[100:103], v[0:15]
	v_mfma_f32_32x32x16_bf16 v[16:31], v[78:81], v[96:99], v[16:31]
	s_waitcnt lgkmcnt(0)
	v_mfma_f32_32x32x16_bf16 v[0:15], v[82:85], v[96:99], v[0:15]
	s_cbranch_scc1 .LBB0_1137
	v_subrev_u32_e32 v49, s67, v181
	v_cmp_gt_u32_e32 vcc, 2.0, v49
	v_add_u32_e32 v50, 0xbfffffe0, v49
	s_nop 5
	v_cndmask_b32_e32 v16, v169, v16, vcc
	v_cmp_lt_u32_e32 vcc, s61, v50
	v_add_u32_e32 v50, 0xbfffffff, v49
	s_nop 0
	v_cndmask_b32_e32 v0, v169, v0, vcc
	v_cmp_lt_u32_e32 vcc, s61, v50
	v_add_u32_e32 v50, 0xbfffffdf, v49
	s_nop 0
	v_cndmask_b32_e32 v17, v169, v17, vcc
	v_cmp_lt_u32_e32 vcc, s61, v50
	v_add_u32_e32 v50, 0xbffffffe, v49
	s_nop 0
	v_cndmask_b32_e32 v1, v169, v1, vcc
	v_cmp_lt_u32_e32 vcc, s61, v50
	v_add_u32_e32 v50, 0xbfffffde, v49
	s_nop 0
	v_cndmask_b32_e32 v18, v169, v18, vcc
	v_cmp_lt_u32_e32 vcc, s61, v50
	v_add_u32_e32 v50, 0xbffffffd, v49
	s_nop 0
	v_cndmask_b32_e32 v2, v169, v2, vcc
	v_cmp_lt_u32_e32 vcc, s61, v50
	v_add_u32_e32 v50, 0xbfffffdd, v49
	s_nop 0
	v_cndmask_b32_e32 v19, v169, v19, vcc
	v_cmp_lt_u32_e32 vcc, s61, v50
	v_add_u32_e32 v50, 0xbffffff8, v49
	s_nop 0
	v_cndmask_b32_e32 v3, v169, v3, vcc
	v_cmp_lt_u32_e32 vcc, s61, v50
	v_add_u32_e32 v50, 0xbfffffd8, v49
	s_nop 0
	v_cndmask_b32_e32 v20, v169, v20, vcc
	v_cmp_lt_u32_e32 vcc, s61, v50
	v_add_u32_e32 v50, 0xbffffff7, v49
	s_nop 0
	v_cndmask_b32_e32 v4, v169, v4, vcc
	v_cmp_lt_u32_e32 vcc, s61, v50
	v_add_u32_e32 v50, 0xbfffffd7, v49
	s_nop 0
	v_cndmask_b32_e32 v21, v169, v21, vcc
	v_cmp_lt_u32_e32 vcc, s61, v50
	v_add_u32_e32 v50, 0xbffffff6, v49
	s_nop 0
	v_cndmask_b32_e32 v5, v169, v5, vcc
	v_cmp_lt_u32_e32 vcc, s61, v50
	v_add_u32_e32 v50, 0xbfffffd6, v49
	s_nop 0
	v_cndmask_b32_e32 v22, v169, v22, vcc
	v_cmp_lt_u32_e32 vcc, s61, v50
	v_add_u32_e32 v50, 0xbffffff5, v49
	s_nop 0
	v_cndmask_b32_e32 v6, v169, v6, vcc
	v_cmp_lt_u32_e32 vcc, s61, v50
	v_add_u32_e32 v50, 0xbfffffd5, v49
	s_nop 0
	v_cndmask_b32_e32 v23, v169, v23, vcc
	v_cmp_lt_u32_e32 vcc, s61, v50
	v_add_u32_e32 v50, 0xbffffff0, v49
	s_nop 0
	v_cndmask_b32_e32 v7, v169, v7, vcc
	v_cmp_lt_u32_e32 vcc, s61, v50
	v_add_u32_e32 v50, 0xbfffffd0, v49
	s_nop 0
	v_cndmask_b32_e32 v24, v169, v24, vcc
	v_cmp_lt_u32_e32 vcc, s61, v50
	v_add_u32_e32 v50, 0xbfffffef, v49
	s_nop 0
	v_cndmask_b32_e32 v8, v169, v8, vcc
	v_cmp_lt_u32_e32 vcc, s61, v50
	v_add_u32_e32 v50, 0xbfffffcf, v49
	s_nop 0
	v_cndmask_b32_e32 v25, v169, v25, vcc
	v_cmp_lt_u32_e32 vcc, s61, v50
	v_add_u32_e32 v50, 0xbfffffee, v49
	s_nop 0
	v_cndmask_b32_e32 v9, v169, v9, vcc
	v_cmp_lt_u32_e32 vcc, s61, v50
	v_add_u32_e32 v50, 0xbfffffce, v49
	s_nop 0
	v_cndmask_b32_e32 v26, v169, v26, vcc
	v_cmp_lt_u32_e32 vcc, s61, v50
	v_add_u32_e32 v50, 0xbfffffed, v49
	s_nop 0
	v_cndmask_b32_e32 v10, v169, v10, vcc
	v_cmp_lt_u32_e32 vcc, s61, v50
	v_add_u32_e32 v50, 0xbfffffcd, v49
	s_nop 0
	v_cndmask_b32_e32 v27, v169, v27, vcc
	v_cmp_lt_u32_e32 vcc, s61, v50
	v_add_u32_e32 v50, 0xbfffffe8, v49
	s_nop 0
	v_cndmask_b32_e32 v11, v169, v11, vcc
	v_cmp_lt_u32_e32 vcc, s61, v50
	v_add_u32_e32 v50, 0xbfffffc8, v49
	s_nop 0
	v_cndmask_b32_e32 v28, v169, v28, vcc
	v_cmp_lt_u32_e32 vcc, s61, v50
	v_add_u32_e32 v50, 0xbfffffe7, v49
	s_nop 0
	v_cndmask_b32_e32 v12, v169, v12, vcc
	v_cmp_lt_u32_e32 vcc, s61, v50
	v_add_u32_e32 v50, 0xbfffffc7, v49
	s_nop 0
	v_cndmask_b32_e32 v29, v169, v29, vcc
	v_cmp_lt_u32_e32 vcc, s61, v50
	v_add_u32_e32 v50, 0xbfffffe6, v49
	s_nop 0
	v_cndmask_b32_e32 v13, v169, v13, vcc
	v_cmp_lt_u32_e32 vcc, s61, v50
	v_add_u32_e32 v50, 0xbfffffc6, v49
	s_nop 0
	v_cndmask_b32_e32 v30, v169, v30, vcc
	v_cmp_lt_u32_e32 vcc, s61, v50
	v_add_u32_e32 v50, 0xbfffffe5, v49
	v_add_u32_e32 v49, 0xbfffffc5, v49
	v_cndmask_b32_e32 v14, v169, v14, vcc
	v_cmp_lt_u32_e32 vcc, s61, v50
	s_nop 1
	v_cndmask_b32_e32 v31, v169, v31, vcc
	v_cmp_lt_u32_e32 vcc, s61, v49
	s_nop 1
	v_cndmask_b32_e32 v15, v169, v15, vcc

; __device__ __forceinline__ void finishSM(f32x16& p0, f32x16& p1, float alpha, float& l_reg, bf16x8& pa0, bf16x8& pa1, bf16x8& pa2, bf16x8& pa3) {
; #pragma unroll
;     for (int r = 0; r < 16; ++r) p1[r] = __builtin_amdgcn_exp2f(p1[r]);
;     float ps = 0;
; #pragma unroll
;     for (int r = 0; r < 16; ++r) ps += p0[r];
; #pragma unroll
;     for (int r = 0; r < 16; ++r) ps += p1[r];
;     { auto rr = __builtin_amdgcn_permlane32_swap(__float_as_uint(ps), __float_as_uint(ps), false, false);
;       ps = __uint_as_float(rr[0]) + __uint_as_float(rr[1]); }
;     l_reg = l_reg * alpha + ps;
;     ...
;     PK4(p0, 0, pa0); PK4(p0, 8, pa1); PK4(p1, 0, pa2); PK4(p1, 8, pa3);
;     ...
; }
; __device__ __forceinline__ void bias_init(f32x16& p0, f32x16& p1, lds_cf bt) {
; #pragma unroll
;     for (int g = 0; g < 4; ++g) { const f32x4 a = *(const __attribute__((address_space(3))) f32x4*)(bt + 8 * g), b = *(const __attribute__((address_space(3))) f32x4*)(bt + 32 + 8 * g);
;         p0[4 * g] = a[0]; p0[4 * g + 1] = a[1]; p0[4 * g + 2] = a[2]; p0[4 * g + 3] = a[3];
;         p1[4 * g] = b[0]; p1[4 * g + 1] = b[1]; p1[4 * g + 2] = b[2]; p1[4 * g + 3] = b[3]; }
; }
; template <int KB>
; __device__ __forceinline__ void qkt(f32x16& p0, f32x16& p1, const char* K_lds, int r32, int hi, const bf16x8* qr, lds_cf bt) {
;     bias_init(p0, p1, bt);
;     const char* kb[4];
; #pragma unroll
;     for (int dd = 0; dd < 4; ++dd) kb[dd] = K_lds + KB * SHM_K + KSWZ(r32, (dd * 16 + hi * 8) * 2);
; #pragma unroll
;     for (int d0 = 0; d0 < 8; ++d0) { const char* a = kb[d0 & 3] + (d0 >> 2) * 128;
;         bf16x8 b0 = *reinterpret_cast<const bf16x8*>(a);
;         bf16x8 b1 = *reinterpret_cast<const bf16x8*>(a + 32 * 256);
;         p0 = __builtin_amdgcn_mfma_f32_32x32x16_bf16(b0, qr[d0], p0, 0, 0, 0);
;         p1 = __builtin_amdgcn_mfma_f32_32x32x16_bf16(b1, qr[d0], p1, 0, 0, 0); }
; }
.LBB0_1141:
	ds_read_b128 v[64:67], v163 offset:49152
	ds_read_b128 v[80:83], v193
	ds_read_b128 v[84:87], v193 offset:32
	ds_read_b128 v[88:91], v193 offset:64
	ds_read_b128 v[92:95], v193 offset:96
	ds_read_b128 v[128:131], v163 offset:57344
	ds_read_b128 v[132:135], v252 offset:49152
	v_exp_f32_e32 v153, v150
	v_exp_f32_e32 v196, v151
	s_waitcnt lgkmcnt(2)
	v_mfma_f32_32x32x16_bf16 v[80:95], v[64:67], v[112:115], v[80:95]
	ds_read_b128 v[64:67], v193 offset:128
	ds_read_b128 v[68:71], v193 offset:160
	ds_read_b128 v[72:75], v193 offset:192
	ds_read_b128 v[76:79], v193 offset:224
	ds_read_b128 v[208:211], v252 offset:57344
	v_exp_f32_e32 v207, v148
	v_exp_f32_e32 v248, v149
	v_exp_f32_e32 v249, v146
	v_exp_f32_e32 v142, v142
	v_exp_f32_e32 v143, v143
	v_exp_f32_e32 v140, v140
	s_waitcnt lgkmcnt(1)
	v_mfma_f32_32x32x16_bf16 v[64:79], v[128:131], v[112:115], v[64:79]
	ds_read_b128 v[128:131], v184 offset:49152
	ds_read_b128 v[212:215], v184 offset:57344
	ds_read_b128 v[216:219], v253 offset:49152
	v_exp_f32_e32 v141, v141
	v_exp_f32_e32 v138, v138
	v_exp_f32_e32 v139, v139
	v_exp_f32_e32 v136, v136
	v_exp_f32_e32 v137, v137
	s_waitcnt lgkmcnt(2)
	v_mfma_f32_32x32x16_bf16 v[80:95], v[128:131], v[116:119], v[80:95]
	ds_read_b128 v[128:131], v253 offset:57344
	ds_read_b128 v[220:223], v185 offset:49152
	ds_read_b128 v[224:227], v254 offset:49152
	ds_read_b128 v[228:231], v185 offset:57344
	ds_read_b128 v[232:235], v254 offset:57344
	ds_read_b128 v[236:239], v186 offset:49152
	ds_read_b128 v[240:243], v255 offset:49152
	s_waitcnt lgkmcnt(8)
	v_mfma_f32_32x32x16_bf16 v[64:79], v[212:215], v[116:119], v[64:79]
	ds_read_b128 v[212:215], v186 offset:57344
	ds_read_b128 v[244:247], v255 offset:57344
	s_waitcnt lgkmcnt(7)
	v_mfma_f32_32x32x16_bf16 v[80:95], v[220:223], v[120:123], v[80:95]
	v_exp_f32_e32 v221, v144
	v_add_f32_e32 v144, 0, v204
	v_add_f32_e32 v144, v206, v144
	v_add_f32_e32 v144, v202, v144
	v_add_f32_e32 v144, v205, v144
	v_add_f32_e32 v144, v201, v144
	v_add_f32_e32 v144, v203, v144
	s_waitcnt lgkmcnt(5)
	v_mfma_f32_32x32x16_bf16 v[64:79], v[228:231], v[120:123], v[64:79]
	v_add_f32_e32 v144, v199, v144
	v_add_f32_e32 v144, v200, v144
	v_add_f32_e32 v144, v157, v144
	v_add_f32_e32 v144, v197, v144
	v_add_f32_e32 v144, v155, v144
	v_add_f32_e32 v144, v158, v144
	v_add_f32_e32 v144, v154, v144
	s_waitcnt lgkmcnt(3)
	v_mfma_f32_32x32x16_bf16 v[80:95], v[236:239], v[124:127], v[80:95]
	v_add_f32_e32 v144, v198, v144
	v_add_f32_e32 v144, v156, v144
	v_add_f32_e32 v144, v159, v144
	v_add_f32_e32 v144, v153, v144
	v_exp_f32_e32 v220, v147
	v_exp_f32_e32 v222, v145
	s_waitcnt lgkmcnt(1)
	v_mfma_f32_32x32x16_bf16 v[64:79], v[212:215], v[124:127], v[64:79]
	v_mfma_f32_32x32x16_bf16 v[80:95], v[132:135], v[108:111], v[80:95]
	v_add_f32_e32 v132, v196, v144
	v_add_f32_e32 v132, v207, v132
	v_add_f32_e32 v132, v248, v132
	v_add_f32_e32 v132, v249, v132
	v_add_f32_e32 v132, v220, v132
	v_add_f32_e32 v132, v221, v132
	v_add_f32_e32 v132, v222, v132
	v_mfma_f32_32x32x16_bf16 v[64:79], v[208:211], v[108:111], v[64:79]
	v_add_f32_e32 v132, v142, v132
	v_add_f32_e32 v132, v143, v132
	v_add_f32_e32 v132, v140, v132
	v_add_f32_e32 v132, v141, v132
	v_add_f32_e32 v132, v138, v132
	v_add_f32_e32 v132, v139, v132
	v_add_f32_e32 v132, v136, v132
	v_mfma_f32_32x32x16_bf16 v[80:95], v[216:219], v[104:107], v[80:95]
	v_add_f32_e32 v194, v137, v132
	v_mov_b32_e32 v195, v194
	s_nop 1
	v_permlane32_swap_b32_e32 v194, v195
	v_cvt_pk_bf16_f32 v144, v204, v206
	v_cvt_pk_bf16_f32 v145, v202, v205
	v_cvt_pk_bf16_f32 v146, v201, v203
	v_mfma_f32_32x32x16_bf16 v[64:79], v[128:131], v[104:107], v[64:79]
	v_cvt_pk_bf16_f32 v147, v199, v200
	v_cvt_pk_bf16_f32 v148, v157, v197
	v_cvt_pk_bf16_f32 v149, v155, v158
	v_cvt_pk_bf16_f32 v150, v154, v198
	v_cvt_pk_bf16_f32 v151, v156, v159
	v_cvt_pk_bf16_f32 v154, v153, v196
	v_cvt_pk_bf16_f32 v155, v207, v248
	v_mfma_f32_32x32x16_bf16 v[80:95], v[224:227], v[100:103], v[80:95]
	v_cvt_pk_bf16_f32 v156, v249, v220
	v_cvt_pk_bf16_f32 v157, v221, v222
	v_cvt_pk_bf16_f32 v200, v142, v143
	v_cvt_pk_bf16_f32 v201, v140, v141
	v_cvt_pk_bf16_f32 v202, v138, v139
	v_cvt_pk_bf16_f32 v203, v136, v137
	v_permlane32_swap_b32_e32 v144, v146
	v_mfma_f32_32x32x16_bf16 v[64:79], v[232:235], v[100:103], v[64:79]
	v_permlane32_swap_b32_e32 v145, v147
	v_permlane32_swap_b32_e32 v148, v150
	v_permlane32_swap_b32_e32 v149, v151
	v_permlane32_swap_b32_e32 v154, v156
	v_mfma_f32_32x32x16_bf16 v[80:95], v[240:243], v[96:99], v[80:95]
	v_permlane32_swap_b32_e32 v155, v157
	v_permlane32_swap_b32_e32 v200, v202
	v_permlane32_swap_b32_e32 v201, v203
	s_waitcnt lgkmcnt(0)
	v_mfma_f32_32x32x16_bf16 v[64:79], v[244:247], v[96:99], v[64:79]
	v_add_u32_e32 v198, s67, v187
	v_add_u32_e32 v128, 1, v198
	v_add_u32_e32 v130, 33, v198
	v_ashrrev_i32_e32 v129, 31, v128
	v_ashrrev_i32_e32 v131, 31, v130
	v_lshlrev_b64 v[136:137], 8, v[128:129]
	v_lshlrev_b64 v[138:139], 8, v[130:131]
	v_lshl_add_u64 v[128:129], v[164:165], 0, v[136:137]
	v_lshl_add_u64 v[132:133], v[164:165], 0, v[138:139]
	v_lshl_add_u64 v[136:137], v[166:167], 0, v[136:137]
	v_lshl_add_u64 v[140:141], v[166:167], 0, v[138:139]
	global_load_dwordx4 v[128:131], v[128:129], off
	s_nop 0
	global_load_dwordx4 v[132:135], v[132:133], off
	s_nop 0
	global_load_dwordx4 v[136:139], v[136:137], off
	s_nop 0
	global_load_dwordx4 v[140:143], v[140:141], off
	ds_read_b64_tr_b16 v[204:205], v180 offset:0
	ds_read_b64_tr_b16 v[206:207], v180 offset:0x800
	ds_read_b64_tr_b16 v[208:209], v180 offset:0x1000
	ds_read_b64_tr_b16 v[210:211], v180 offset:0x1800
	ds_read_b64_tr_b16 v[212:213], v180 offset:0x2000
	ds_read_b64_tr_b16 v[214:215], v180 offset:0x2800
	ds_read_b64_tr_b16 v[216:217], v180 offset:0x3000
	ds_read_b64_tr_b16 v[218:219], v180 offset:0x3800
	s_waitcnt lgkmcnt(0)
; __device__ __forceinline__ void mask_tile(f32x16& p0, f32x16& p1, int dq, unsigned W) {
;     const float NEG = -__builtin_inff();
; #pragma unroll
;     for (int r = 0; r < 16; ++r) { const int c = (r & 3) + 8 * (r >> 2);
;         if ((unsigned)(dq - c) >= W) p0[r] = NEG;
;         if ((unsigned)(dq - c - 32) >= W) p1[r] = NEG; }
; }
; template <int VB>
; __device__ __forceinline__ void pv_tile(f32x16* o, int vb0, bf16x8 pa0, bf16x8 pa1, bf16x8 pa2, bf16x8 pa3) {
;     ...
;     PV_D0(0); PV_D0(1); PV_D0(2); PV_D0(3);
;     ...
; }
	s_nop 0
	v_mfma_f32_32x32x16_bf16 v[48:63], v[144:147], v[204:207], v[48:63]
	ds_read_b64_tr_b16 v[204:205], v180 offset:0x200
	ds_read_b64_tr_b16 v[206:207], v180 offset:0xa00
	v_mfma_f32_32x32x16_bf16 v[48:63], v[148:151], v[208:211], v[48:63]
	ds_read_b64_tr_b16 v[208:209], v180 offset:0x1200
	ds_read_b64_tr_b16 v[210:211], v180 offset:0x1a00
	v_mfma_f32_32x32x16_bf16 v[48:63], v[154:157], v[212:215], v[48:63]
	ds_read_b64_tr_b16 v[212:213], v180 offset:0x2200
	ds_read_b64_tr_b16 v[214:215], v180 offset:0x2a00
	ds_read_b64_tr_b16 v[220:221], v180 offset:0x3200
	ds_read_b64_tr_b16 v[222:223], v180 offset:0x3a00
	s_waitcnt lgkmcnt(0)
	v_mfma_f32_32x32x16_bf16 v[48:63], v[200:203], v[216:219], v[48:63]
	v_mfma_f32_32x32x16_bf16 v[32:47], v[144:147], v[204:207], v[32:47]
	ds_read_b64_tr_b16 v[204:205], v180 offset:0x400
	ds_read_b64_tr_b16 v[206:207], v180 offset:0xc00
	v_mfma_f32_32x32x16_bf16 v[32:47], v[148:151], v[208:211], v[32:47]
	ds_read_b64_tr_b16 v[208:209], v180 offset:0x1400
	ds_read_b64_tr_b16 v[210:211], v180 offset:0x1c00
	v_mfma_f32_32x32x16_bf16 v[32:47], v[154:157], v[212:215], v[32:47]
	ds_read_b64_tr_b16 v[212:213], v180 offset:0x2400
	ds_read_b64_tr_b16 v[214:215], v180 offset:0x2c00
	ds_read_b64_tr_b16 v[216:217], v180 offset:0x3400
	ds_read_b64_tr_b16 v[218:219], v180 offset:0x3c00
	s_waitcnt lgkmcnt(0)
	v_mfma_f32_32x32x16_bf16 v[32:47], v[200:203], v[220:223], v[32:47]
	v_mfma_f32_32x32x16_bf16 v[16:31], v[144:147], v[204:207], v[16:31]
	ds_read_b64_tr_b16 v[204:205], v180 offset:0x600
	ds_read_b64_tr_b16 v[206:207], v180 offset:0xe00
	v_mfma_f32_32x32x16_bf16 v[16:31], v[148:151], v[208:211], v[16:31]
	ds_read_b64_tr_b16 v[208:209], v180 offset:0x1600
	ds_read_b64_tr_b16 v[210:211], v180 offset:0x1e00
	v_mfma_f32_32x32x16_bf16 v[16:31], v[154:157], v[212:215], v[16:31]
	ds_read_b64_tr_b16 v[212:213], v180 offset:0x2600
	ds_read_b64_tr_b16 v[214:215], v180 offset:0x2e00
	ds_read_b64_tr_b16 v[220:221], v180 offset:0x3600
	ds_read_b64_tr_b16 v[222:223], v180 offset:0x3e00
	s_waitcnt lgkmcnt(0)
	v_mfma_f32_32x32x16_bf16 v[16:31], v[200:203], v[216:219], v[16:31]
	v_mfma_f32_32x32x16_bf16 v[0:15], v[144:147], v[204:207], v[0:15]
	s_cmp_le_i32 s67, s45
	v_mfma_f32_32x32x16_bf16 v[0:15], v[148:151], v[208:211], v[0:15]
	v_mfma_f32_32x32x16_bf16 v[0:15], v[154:157], v[212:215], v[0:15]
	v_mfma_f32_32x32x16_bf16 v[0:15], v[200:203], v[220:223], v[0:15]
	s_cbranch_scc1 .LBB0_1143
	v_add_u32_e32 v144, 0x4000007b, v192
	v_cmp_gt_u32_e32 vcc, 2.0, v144
	v_add_u32_e32 v144, 0x5b, v192
	s_nop 0
	v_cndmask_b32_e32 v80, v169, v80, vcc
	v_cmp_lt_u32_e32 vcc, s61, v144
	v_add_u32_e32 v144, 0x7a, v192
	s_nop 0
	v_cndmask_b32_e32 v64, v169, v64, vcc
	v_cmp_lt_u32_e32 vcc, s61, v144
	v_add_u32_e32 v144, 0x5a, v192
	s_nop 0
	v_cndmask_b32_e32 v81, v169, v81, vcc
	v_cmp_lt_u32_e32 vcc, s61, v144
	v_add_u32_e32 v144, 0x79, v192
	s_nop 0
	v_cndmask_b32_e32 v65, v169, v65, vcc
	v_cmp_lt_u32_e32 vcc, s61, v144
	v_add_u32_e32 v144, 0x59, v192
	s_nop 0
	v_cndmask_b32_e32 v82, v169, v82, vcc
	v_cmp_lt_u32_e32 vcc, s61, v144
	v_add_u32_e32 v144, 0x78, v192
	s_nop 0
	v_cndmask_b32_e32 v66, v169, v66, vcc
	v_cmp_lt_u32_e32 vcc, s61, v144
	v_add_u32_e32 v144, 0x58, v192
	s_nop 0
	v_cndmask_b32_e32 v83, v169, v83, vcc
	v_cmp_lt_u32_e32 vcc, s61, v144
	v_add_u32_e32 v144, 0x73, v192
	s_nop 0
	v_cndmask_b32_e32 v67, v169, v67, vcc
	v_cmp_lt_u32_e32 vcc, s61, v144
	v_add_u32_e32 v144, 0x53, v192
	s_nop 0
	v_cndmask_b32_e32 v84, v169, v84, vcc
	v_cmp_lt_u32_e32 vcc, s61, v144
	v_add_u32_e32 v144, 0x72, v192
	s_nop 0
	v_cndmask_b32_e32 v68, v169, v68, vcc
	v_cmp_lt_u32_e32 vcc, s61, v144
	v_add_u32_e32 v144, 0x52, v192
	s_nop 0
	v_cndmask_b32_e32 v85, v169, v85, vcc
	v_cmp_lt_u32_e32 vcc, s61, v144
	v_add_u32_e32 v144, 0x71, v192
	s_nop 0
	v_cndmask_b32_e32 v69, v169, v69, vcc
	v_cmp_lt_u32_e32 vcc, s61, v144
	v_add_u32_e32 v144, 0x51, v192
	s_nop 0
	v_cndmask_b32_e32 v86, v169, v86, vcc
	v_cmp_lt_u32_e32 vcc, s61, v144
	v_add_u32_e32 v144, 0x70, v192
	s_nop 0
	v_cndmask_b32_e32 v70, v169, v70, vcc
	v_cmp_lt_u32_e32 vcc, s61, v144
	v_add_u32_e32 v144, 0x50, v192
	s_nop 0
	v_cndmask_b32_e32 v87, v169, v87, vcc
	v_cmp_lt_u32_e32 vcc, s61, v144
	v_add_u32_e32 v144, 0x6b, v192
	s_nop 0
	v_cndmask_b32_e32 v71, v169, v71, vcc
	v_cmp_lt_u32_e32 vcc, s61, v144
	v_add_u32_e32 v144, 0x4b, v192
	s_nop 0
	v_cndmask_b32_e32 v88, v169, v88, vcc
	v_cmp_lt_u32_e32 vcc, s61, v144
	v_add_u32_e32 v144, 0x6a, v192
	s_nop 0
	v_cndmask_b32_e32 v72, v169, v72, vcc
	v_cmp_lt_u32_e32 vcc, s61, v144
	v_add_u32_e32 v144, 0x4a, v192
	s_nop 0
	v_cndmask_b32_e32 v89, v169, v89, vcc
	v_cmp_lt_u32_e32 vcc, s61, v144
	v_add_u32_e32 v144, 0x69, v192
	s_nop 0
	v_cndmask_b32_e32 v73, v169, v73, vcc
	v_cmp_lt_u32_e32 vcc, s61, v144
	v_add_u32_e32 v144, 0x49, v192
	s_nop 0
	v_cndmask_b32_e32 v90, v169, v90, vcc
	v_cmp_lt_u32_e32 vcc, s61, v144
	v_add_u32_e32 v144, 0x68, v192
	s_nop 0
	v_cndmask_b32_e32 v74, v169, v74, vcc
	v_cmp_lt_u32_e32 vcc, s61, v144
	v_add_u32_e32 v144, 0x48, v192
	s_nop 0
	v_cndmask_b32_e32 v91, v169, v91, vcc
	v_cmp_lt_u32_e32 vcc, s61, v144
	v_add_u32_e32 v144, 0x63, v192
	s_nop 0
	v_cndmask_b32_e32 v75, v169, v75, vcc
	v_cmp_lt_u32_e32 vcc, s61, v144
	v_add_u32_e32 v144, 0x43, v192
	s_nop 0
	v_cndmask_b32_e32 v92, v169, v92, vcc
	v_cmp_lt_u32_e32 vcc, s61, v144
	v_add_u32_e32 v144, 0x62, v192
	s_nop 0
	v_cndmask_b32_e32 v76, v169, v76, vcc
	v_cmp_lt_u32_e32 vcc, s61, v144
	v_add_u32_e32 v144, 0x42, v192
	s_nop 0
	v_cndmask_b32_e32 v93, v169, v93, vcc
	v_cmp_lt_u32_e32 vcc, s61, v144
	v_add_u32_e32 v144, 0x61, v192
	s_nop 0
	v_cndmask_b32_e32 v77, v169, v77, vcc
	v_cmp_lt_u32_e32 vcc, s61, v144
	v_add_u32_e32 v144, 0x41, v192
	s_nop 0
	v_cndmask_b32_e32 v94, v169, v94, vcc
	v_cmp_lt_u32_e32 vcc, s61, v144
	v_add_u32_e32 v144, 0x60, v192
	s_nop 0
	v_cndmask_b32_e32 v78, v169, v78, vcc
	v_cmp_lt_u32_e32 vcc, s61, v144
	v_add_u32_e32 v144, 64, v192
	s_nop 0
	v_cndmask_b32_e32 v95, v169, v95, vcc
	v_cmp_lt_u32_e32 vcc, s61, v144
	s_nop 1
	v_cndmask_b32_e32 v79, v169, v79, vcc

; __device__ __forceinline__ void partialSM(f32x16& p0, f32x16& p1, float& m_reg, float& mn, float& alpha) {
;     float pmax = p0[0];
; #pragma unroll
;     for (int r = 1; r < 16; ++r) pmax = fmaxf(pmax, p0[r]);
; #pragma unroll
;     for (int r = 0; r < 16; ++r) pmax = fmaxf(pmax, p1[r]);
;     { auto rr = __builtin_amdgcn_permlane32_swap(__float_as_uint(pmax), __float_as_uint(pmax), false, false);
;       pmax = fmaxf(__uint_as_float(rr[0]), __uint_as_float(rr[1])); }
;     constexpr float C2 = 1.4426950408889634f * SCALE;
;     if (__builtin_expect(__all((pmax - m_reg) * SCALE <= THR), 1)) { mn = m_reg; alpha = 1.f; }
;     else { mn = fmaxf(m_reg, pmax); alpha = __builtin_amdgcn_exp2f((m_reg - mn) * C2); m_reg = mn; }
;     const float mnL = -mn * C2;
; #pragma unroll
;     for (int r = 0; r < 16; ++r) p0[r] = fmaf(p0[r], C2, mnL);
; #pragma unroll
;     for (int r = 0; r < 16; ++r) p1[r] = fmaf(p1[r], C2, mnL);
; #pragma unroll
;     for (int r = 0; r < 16; ++r) p0[r] = __builtin_amdgcn_exp2f(p0[r]);
; }
; __device__ __forceinline__ void finishSM(f32x16& p0, f32x16& p1, float alpha, float& l_reg, bf16x8& pa0, bf16x8& pa1, bf16x8& pa2, bf16x8& pa3) {
; #pragma unroll
;     for (int r = 0; r < 16; ++r) p1[r] = __builtin_amdgcn_exp2f(p1[r]);
;     float ps = 0;
; #pragma unroll
;     for (int r = 0; r < 16; ++r) ps += p0[r];
; #pragma unroll
;     for (int r = 0; r < 16; ++r) ps += p1[r];
;     { auto rr = __builtin_amdgcn_permlane32_swap(__float_as_uint(ps), __float_as_uint(ps), false, false);
;       ps = __uint_as_float(rr[0]) + __uint_as_float(rr[1]); }
;     l_reg = l_reg * alpha + ps;
;     ...
;     PK4(p0, 0, pa0); PK4(p0, 8, pa1); PK4(p1, 0, pa2); PK4(p1, 8, pa3);
;     ...
; }
; __device__ __forceinline__ void bias_init(f32x16& p0, f32x16& p1, lds_cf bt) {
; #pragma unroll
;     for (int g = 0; g < 4; ++g) { const f32x4 a = *(const __attribute__((address_space(3))) f32x4*)(bt + 8 * g), b = *(const __attribute__((address_space(3))) f32x4*)(bt + 32 + 8 * g);
;         p0[4 * g] = a[0]; p0[4 * g + 1] = a[1]; p0[4 * g + 2] = a[2]; p0[4 * g + 3] = a[3];
;         p1[4 * g] = b[0]; p1[4 * g + 1] = b[1]; p1[4 * g + 2] = b[2]; p1[4 * g + 3] = b[3]; }
; }
; template <int KB>
; __device__ __forceinline__ void qkt(f32x16& p0, f32x16& p1, const char* K_lds, int r32, int hi, const bf16x8* qr, lds_cf bt) {
;     bias_init(p0, p1, bt);
;     const char* kb[4];
; #pragma unroll
.LBB0_1147:
	v_cndmask_b32_e64 v197, v144, v152, s[8:9]
	v_mul_f32_e32 v199, 0xbe0293ee, v197
	v_fmamk_f32 v80, v80, 0x3e0293ee, v199
	v_fmamk_f32 v81, v81, 0x3e0293ee, v199
	v_fmamk_f32 v82, v82, 0x3e0293ee, v199
	v_fmamk_f32 v83, v83, 0x3e0293ee, v199
	v_fmamk_f32 v84, v84, 0x3e0293ee, v199
	v_fmamk_f32 v85, v85, 0x3e0293ee, v199
	v_fmamk_f32 v86, v86, 0x3e0293ee, v199
	v_fmamk_f32 v87, v87, 0x3e0293ee, v199
	v_fmamk_f32 v88, v88, 0x3e0293ee, v199
	v_fmamk_f32 v89, v89, 0x3e0293ee, v199
	v_fmamk_f32 v90, v90, 0x3e0293ee, v199
	v_fmamk_f32 v91, v91, 0x3e0293ee, v199
	v_fmamk_f32 v92, v92, 0x3e0293ee, v199
	v_fmamk_f32 v93, v93, 0x3e0293ee, v199
	v_fmamk_f32 v94, v94, 0x3e0293ee, v199
	v_fmamk_f32 v95, v95, 0x3e0293ee, v199
	v_exp_f32_e32 v144, v80
	v_exp_f32_e32 v159, v81
	v_exp_f32_e32 v145, v82
	v_exp_f32_e32 v158, v83
	v_exp_f32_e32 v146, v84
	v_exp_f32_e32 v157, v85
	v_exp_f32_e32 v147, v86
	v_exp_f32_e32 v156, v87
	v_exp_f32_e32 v148, v88
	v_exp_f32_e32 v155, v89
	v_exp_f32_e32 v149, v90
	v_exp_f32_e32 v154, v91
	v_exp_f32_e32 v150, v92
	v_exp_f32_e32 v153, v93
	v_exp_f32_e32 v151, v94
	v_exp_f32_e32 v152, v95
	v_fmamk_f32 v208, v64, 0x3e0293ee, v199
	v_fmamk_f32 v207, v75, 0x3e0293ee, v199
	v_fmamk_f32 v209, v65, 0x3e0293ee, v199
	v_fmamk_f32 v210, v66, 0x3e0293ee, v199
	v_fmamk_f32 v211, v67, 0x3e0293ee, v199
	v_fmamk_f32 v212, v68, 0x3e0293ee, v199
	v_fmamk_f32 v201, v69, 0x3e0293ee, v199
	v_fmamk_f32 v202, v70, 0x3e0293ee, v199
	v_fmamk_f32 v203, v71, 0x3e0293ee, v199
	v_fmamk_f32 v204, v72, 0x3e0293ee, v199
	v_fmamk_f32 v205, v73, 0x3e0293ee, v199
	v_fmamk_f32 v206, v74, 0x3e0293ee, v199
	v_fmamk_f32 v200, v76, 0x3e0293ee, v199
	v_fmamk_f32 v213, v77, 0x3e0293ee, v199
	v_fmamk_f32 v214, v78, 0x3e0293ee, v199
	v_fmac_f32_e32 v199, 0x3e0293ee, v79
	s_waitcnt lgkmcnt(0)
	ds_read_b128 v[80:83], v193 offset:256
	ds_read_b128 v[84:87], v193 offset:288
	ds_read_b128 v[64:67], v193 offset:384
	ds_read_b128 v[68:71], v193 offset:416
	ds_read_b128 v[88:91], v193 offset:320
	ds_read_b128 v[72:75], v193 offset:448
	ds_read_b128 v[92:95], v193 offset:352
	ds_read_b128 v[76:79], v193 offset:480
	ds_read_b128 v[216:219], v163 offset:32768
	ds_read_b128 v[220:223], v163 offset:40960
	v_exp_f32_e32 v215, v208
	v_exp_f32_e32 v209, v209
	v_exp_f32_e32 v210, v210
	s_waitcnt lgkmcnt(1)
	v_mfma_f32_32x32x16_bf16 v[80:95], v[216:219], v[112:115], v[80:95]
	v_exp_f32_e32 v211, v211
	v_exp_f32_e32 v212, v212
	v_exp_f32_e32 v201, v201
	v_exp_f32_e32 v202, v202
	v_exp_f32_e32 v203, v203
	v_exp_f32_e32 v204, v204
	v_exp_f32_e32 v205, v205
	s_waitcnt lgkmcnt(0)
	v_mfma_f32_32x32x16_bf16 v[64:79], v[220:223], v[112:115], v[64:79]
	ds_read_b128 v[216:219], v184 offset:32768
	ds_read_b128 v[220:223], v184 offset:40960
	v_exp_f32_e32 v206, v206
	v_exp_f32_e32 v200, v200
	v_exp_f32_e32 v213, v213
	v_exp_f32_e32 v214, v214
	v_exp_f32_e32 v199, v199
	s_waitcnt lgkmcnt(1)
	v_mfma_f32_32x32x16_bf16 v[80:95], v[216:219], v[116:119], v[80:95]
	s_waitcnt lgkmcnt(0)
	v_mfma_f32_32x32x16_bf16 v[64:79], v[220:223], v[116:119], v[64:79]
	ds_read_b128 v[216:219], v185 offset:32768
	ds_read_b128 v[220:223], v185 offset:40960
	s_waitcnt lgkmcnt(1)
	v_mfma_f32_32x32x16_bf16 v[80:95], v[216:219], v[120:123], v[80:95]
	s_waitcnt lgkmcnt(0)
	v_mfma_f32_32x32x16_bf16 v[64:79], v[220:223], v[120:123], v[64:79]
	ds_read_b128 v[216:219], v186 offset:32768
	ds_read_b128 v[220:223], v186 offset:40960
	s_waitcnt lgkmcnt(1)
	v_mfma_f32_32x32x16_bf16 v[80:95], v[216:219], v[124:127], v[80:95]
	s_waitcnt lgkmcnt(0)
	v_mfma_f32_32x32x16_bf16 v[64:79], v[220:223], v[124:127], v[64:79]
	ds_read_b128 v[216:219], v252 offset:32768
	ds_read_b128 v[220:223], v252 offset:40960
	s_waitcnt lgkmcnt(1)
	v_mfma_f32_32x32x16_bf16 v[80:95], v[216:219], v[108:111], v[80:95]
	s_waitcnt lgkmcnt(0)
	v_mfma_f32_32x32x16_bf16 v[64:79], v[220:223], v[108:111], v[64:79]
	ds_read_b128 v[216:219], v253 offset:32768
	ds_read_b128 v[220:223], v253 offset:40960
	s_waitcnt lgkmcnt(1)
	v_mfma_f32_32x32x16_bf16 v[80:95], v[216:219], v[104:107], v[80:95]
	s_waitcnt lgkmcnt(0)
	v_mfma_f32_32x32x16_bf16 v[64:79], v[220:223], v[104:107], v[64:79]
	ds_read_b128 v[216:219], v254 offset:32768
	ds_read_b128 v[220:223], v254 offset:40960
	s_waitcnt lgkmcnt(1)
	v_mfma_f32_32x32x16_bf16 v[80:95], v[216:219], v[100:103], v[80:95]
	s_waitcnt lgkmcnt(0)
	v_mfma_f32_32x32x16_bf16 v[64:79], v[220:223], v[100:103], v[64:79]
	ds_read_b128 v[216:219], v255 offset:32768
	ds_read_b128 v[220:223], v255 offset:40960
	s_waitcnt lgkmcnt(1)
	v_mfma_f32_32x32x16_bf16 v[80:95], v[216:219], v[96:99], v[80:95]
	v_exp_f32_e32 v216, v207
	v_add_f32_e32 v207, 0, v144
	v_add_f32_e32 v207, v159, v207
	v_add_f32_e32 v207, v145, v207
	v_add_f32_e32 v207, v158, v207
	v_add_f32_e32 v207, v146, v207
	v_add_f32_e32 v207, v157, v207
	v_add_f32_e32 v207, v147, v207
	v_add_f32_e32 v207, v156, v207
	v_add_f32_e32 v207, v148, v207
	v_add_f32_e32 v207, v155, v207
	v_add_f32_e32 v207, v149, v207
	v_add_f32_e32 v207, v154, v207
	v_add_f32_e32 v207, v150, v207
	v_add_f32_e32 v207, v153, v207
	v_add_f32_e32 v207, v151, v207
	v_add_f32_e32 v207, v152, v207
	v_add_f32_e32 v207, v215, v207
	v_add_f32_e32 v207, v209, v207
	v_add_f32_e32 v207, v210, v207
	v_add_f32_e32 v207, v211, v207
	v_add_f32_e32 v207, v212, v207
	v_add_f32_e32 v207, v201, v207
	v_add_f32_e32 v207, v202, v207
	v_add_f32_e32 v207, v203, v207
	v_add_f32_e32 v207, v204, v207
	v_add_f32_e32 v207, v205, v207
	s_waitcnt lgkmcnt(0)
	v_mfma_f32_32x32x16_bf16 v[64:79], v[220:223], v[96:99], v[64:79]
	v_add_f32_e32 v207, v206, v207
	v_add_f32_e32 v207, v216, v207
	v_add_f32_e32 v207, v200, v207
	v_add_f32_e32 v207, v213, v207
	v_add_f32_e32 v207, v214, v207
	v_add_f32_e32 v207, v199, v207
	v_mov_b32_e32 v208, v207
	v_cvt_pk_bf16_f32 v144, v144, v159
	v_cvt_pk_bf16_f32 v145, v145, v158
	v_cvt_pk_bf16_f32 v146, v146, v157
	v_cvt_pk_bf16_f32 v147, v147, v156
	v_cvt_pk_bf16_f32 v148, v148, v155
	v_cvt_pk_bf16_f32 v149, v149, v154
	v_cvt_pk_bf16_f32 v150, v150, v153
	v_cvt_pk_bf16_f32 v151, v151, v152
	v_cvt_pk_bf16_f32 v152, v215, v209
	v_cvt_pk_bf16_f32 v153, v210, v211
	v_cvt_pk_bf16_f32 v154, v212, v201
	v_cvt_pk_bf16_f32 v155, v202, v203
	v_cvt_pk_bf16_f32 v156, v204, v205
	v_cvt_pk_bf16_f32 v157, v206, v216
	v_cvt_pk_bf16_f32 v158, v200, v213
	v_cvt_pk_bf16_f32 v159, v214, v199
	s_nop 1
	v_permlane32_swap_b32_e32 v207, v208
	v_permlane32_swap_b32_e32 v144, v146
	v_permlane32_swap_b32_e32 v145, v147
	v_permlane32_swap_b32_e32 v148, v150
	v_permlane32_swap_b32_e32 v149, v151
	v_permlane32_swap_b32_e32 v152, v154
	v_permlane32_swap_b32_e32 v153, v155
	v_permlane32_swap_b32_e32 v156, v158
	v_permlane32_swap_b32_e32 v157, v159
	s_add_i32 s8, s66, 1
	s_cmp_lt_i32 s8, s65
	s_cselect_b64 s[58:59], -1, 0
	s_cmp_ge_i32 s8, s65
	s_cbranch_scc1 .LBB0_1149
	v_add_u32_e32 v128, 0x41, v198
	v_add_u32_e32 v130, 0x61, v198
	v_ashrrev_i32_e32 v129, 31, v128
	v_ashrrev_i32_e32 v131, 31, v130
	v_lshlrev_b64 v[136:137], 8, v[128:129]
	v_lshlrev_b64 v[138:139], 8, v[130:131]
	v_lshl_add_u64 v[128:129], v[164:165], 0, v[136:137]
	v_lshl_add_u64 v[132:133], v[164:165], 0, v[138:139]
	v_lshl_add_u64 v[136:137], v[166:167], 0, v[136:137]
	v_lshl_add_u64 v[140:141], v[166:167], 0, v[138:139]
	global_load_dwordx4 v[128:131], v[128:129], off
	s_nop 0
	global_load_dwordx4 v[132:135], v[132:133], off
	s_nop 0
	global_load_dwordx4 v[136:139], v[136:137], off
	s_nop 0
	global_load_dwordx4 v[140:143], v[140:141], off

; #define SBAR() __builtin_amdgcn_sched_barrier(0)
; __device__ __forceinline__ void finishSM(f32x16& p0, f32x16& p1, float alpha, float& l_reg, bf16x8& pa0, bf16x8& pa1, bf16x8& pa2, bf16x8& pa3) {
; #pragma unroll
;     for (int r = 0; r < 16; ++r) p1[r] = __builtin_amdgcn_exp2f(p1[r]);
;     float ps = 0;
; #pragma unroll
;     for (int r = 0; r < 16; ++r) ps += p0[r];
; #pragma unroll
;     for (int r = 0; r < 16; ++r) ps += p1[r];
;     { auto rr = __builtin_amdgcn_permlane32_swap(__float_as_uint(ps), __float_as_uint(ps), false, false);
;       ps = __uint_as_float(rr[0]) + __uint_as_float(rr[1]); }
;     l_reg = l_reg * alpha + ps;
;     ...
;     PK4(p0, 0, pa0); PK4(p0, 8, pa1); PK4(p1, 0, pa2); PK4(p1, 8, pa3);
;     ...
; }
; __device__ __forceinline__ void bias_init(f32x16& p0, f32x16& p1, lds_cf bt) {
; #pragma unroll
;     for (int g = 0; g < 4; ++g) { const f32x4 a = *(const __attribute__((address_space(3))) f32x4*)(bt + 8 * g), b = *(const __attribute__((address_space(3))) f32x4*)(bt + 32 + 8 * g);
;         p0[4 * g] = a[0]; p0[4 * g + 1] = a[1]; p0[4 * g + 2] = a[2]; p0[4 * g + 3] = a[3];
;         p1[4 * g] = b[0]; p1[4 * g + 1] = b[1]; p1[4 * g + 2] = b[2]; p1[4 * g + 3] = b[3]; }
; }
; template <int KB>
; __device__ __forceinline__ void qkt(f32x16& p0, f32x16& p1, const char* K_lds, int r32, int hi, const bf16x8* qr, lds_cf bt) {
;     bias_init(p0, p1, bt);
;     const char* kb[4];
; #pragma unroll
;     for (int dd = 0; dd < 4; ++dd) kb[dd] = K_lds + KB * SHM_K + KSWZ(r32, (dd * 16 + hi * 8) * 2);
; #pragma unroll
;     for (int d0 = 0; d0 < 8; ++d0) { const char* a = kb[d0 & 3] + (d0 >> 2) * 128;
;         bf16x8 b0 = *reinterpret_cast<const bf16x8*>(a);
;         bf16x8 b1 = *reinterpret_cast<const bf16x8*>(a + 32 * 256);
;         p0 = __builtin_amdgcn_mfma_f32_32x32x16_bf16(b0, qr[d0], p0, 0, 0, 0);
;         p1 = __builtin_amdgcn_mfma_f32_32x32x16_bf16(b1, qr[d0], p1, 0, 0, 0); }
; }
; __device__ __forceinline__ void block(const BlockRef& cur, const BlockRef& nxt, char* lds, Seam& S) {
;     ...
;     SBAR(); qkt<1>(pB0, pB1, K_lds, r32, hi, S.qr, bt0 + KBASE(NT - 1)); SBAR();
; #pragma unroll
;     for (int d0 = 0; d0 < 8; ++d0) S.qr[d0] = load8h(nxt.Qp() + (size_t)(wid * QBLK + r32) * D + d0 * 16 + hi * 8);
;     SBAR();
;     finishSM(pA0, pA1, alA, l_reg, pa0, pa1, pa2, pa3); SBAR();
;     pv_tile<0>(o, vb0, pa0, pa1, pa2, pa3);
.LBB0_1160:
	s_and_b32 s7, s43, 0xffffffc0
	s_sub_i32 s6, s7, 64
	v_lshl_add_u32 v92, s6, 2, v183
	ds_read_b128 v[80:83], v163 offset:49152
	ds_read_b128 v[64:67], v92
	ds_read_b128 v[68:71], v92 offset:32
	ds_read_b128 v[72:75], v92 offset:64
	ds_read_b128 v[76:79], v92 offset:96
	ds_read_b128 v[84:87], v252 offset:49152
	s_waitcnt lgkmcnt(1)
	v_mfma_f32_32x32x16_bf16 v[64:79], v[80:83], v[112:115], v[64:79]
	ds_read_b128 v[80:83], v184 offset:49152
	ds_read_b128 v[88:91], v253 offset:49152
	s_waitcnt lgkmcnt(1)
	v_mfma_f32_32x32x16_bf16 v[64:79], v[80:83], v[116:119], v[64:79]
	ds_read_b128 v[80:83], v185 offset:49152
	ds_read_b128 v[128:131], v254 offset:49152
	s_waitcnt lgkmcnt(1)
	v_mfma_f32_32x32x16_bf16 v[64:79], v[80:83], v[120:123], v[64:79]
	ds_read_b128 v[80:83], v186 offset:49152
	ds_read_b128 v[132:135], v255 offset:49152
	s_waitcnt lgkmcnt(1)
	v_mfma_f32_32x32x16_bf16 v[64:79], v[80:83], v[124:127], v[64:79]
	v_mfma_f32_32x32x16_bf16 v[64:79], v[84:87], v[108:111], v[64:79]
	v_mfma_f32_32x32x16_bf16 v[64:79], v[88:91], v[104:107], v[64:79]
	ds_read_b128 v[80:83], v92 offset:128
	ds_read_b128 v[84:87], v92 offset:160
	ds_read_b128 v[88:91], v92 offset:192
	ds_read_b128 v[92:95], v92 offset:224
	v_mfma_f32_32x32x16_bf16 v[64:79], v[128:131], v[100:103], v[64:79]
	ds_read_b128 v[128:131], v163 offset:57344
	ds_read_b128 v[164:167], v252 offset:57344
	ds_read_b128 v[188:191], v184 offset:57344
	ds_read_b128 v[192:195], v253 offset:57344
	ds_read_b128 v[208:211], v185 offset:57344
	ds_read_b128 v[212:215], v254 offset:57344
	ds_read_b128 v[216:219], v186 offset:57344
	ds_read_b128 v[184:187], v255 offset:57344
	s_waitcnt lgkmcnt(12)
	v_mfma_f32_32x32x16_bf16 v[64:79], v[132:135], v[96:99], v[64:79]
	s_waitcnt lgkmcnt(7)
	v_mfma_f32_32x32x16_bf16 v[80:95], v[128:131], v[112:115], v[80:95]
	s_mov_b32 s43, s57
	s_lshl_b64 s[8:9], s[42:43], 8
	s_add_u32 s8, s36, s8
	s_addc_u32 s9, s37, s9
	v_mov_b32_e32 v163, v161
	s_waitcnt lgkmcnt(5)
	v_mfma_f32_32x32x16_bf16 v[80:95], v[188:191], v[116:119], v[80:95]
	s_waitcnt lgkmcnt(3)
	v_mfma_f32_32x32x16_bf16 v[80:95], v[208:211], v[120:123], v[80:95]
	s_waitcnt lgkmcnt(1)
	v_mfma_f32_32x32x16_bf16 v[80:95], v[216:219], v[124:127], v[80:95]
	v_mfma_f32_32x32x16_bf16 v[80:95], v[164:167], v[108:111], v[80:95]
	v_or_b32_e32 v108, s44, v177
	v_ashrrev_i32_e32 v109, 31, v108
	v_lshlrev_b64 v[108:109], 8, v[108:109]
	v_lshl_add_u64 v[108:109], s[8:9], 0, v[108:109]
	v_lshl_add_u64 v[108:109], v[108:109], 0, v[162:163]
	v_lshl_add_u64 v[132:133], v[108:109], 0, s[28:29]
	v_add_co_u32_e32 v112, vcc, s51, v108
	v_mfma_f32_32x32x16_bf16 v[80:95], v[192:195], v[104:107], v[80:95]
	s_nop 0
	v_addc_co_u32_e32 v113, vcc, -1, v109, vcc
	global_load_dwordx4 v[116:119], v[132:133], off offset:32
	global_load_dwordx4 v[120:123], v[132:133], off offset:64
	global_load_dwordx4 v[124:127], v[132:133], off offset:96
	global_load_dwordx4 v[108:111], v[132:133], off offset:128
	global_load_dwordx4 v[104:107], v[132:133], off offset:160
	global_load_dwordx4 v[128:131], v[132:133], off offset:192
	s_nop 0
	global_load_dwordx4 v[112:115], v[112:113], off
	s_nop 0
	global_load_dwordx4 v[132:135], v[132:133], off offset:224
	v_mfma_f32_32x32x16_bf16 v[80:95], v[212:215], v[100:103], v[80:95]
	s_waitcnt lgkmcnt(0)
	v_mfma_f32_32x32x16_bf16 v[80:95], v[184:187], v[96:99], v[80:95]
	v_add_f32_e32 v96, 0, v204
	v_add_f32_e32 v96, v206, v96
	v_add_f32_e32 v96, v202, v96
	v_add_f32_e32 v96, v205, v96
	v_add_f32_e32 v96, v201, v96
	v_add_f32_e32 v96, v203, v96
	v_add_f32_e32 v96, v199, v96
	v_add_f32_e32 v96, v200, v96
	v_add_f32_e32 v96, v157, v96
	v_add_f32_e32 v96, v197, v96
	v_add_f32_e32 v96, v155, v96
	v_add_f32_e32 v96, v158, v96
	v_exp_f32_e32 v102, v150
	v_add_f32_e32 v96, v154, v96
	v_exp_f32_e32 v103, v151
	v_add_f32_e32 v96, v198, v96
	v_exp_f32_e32 v148, v148
	v_add_f32_e32 v96, v156, v96
	v_exp_f32_e32 v149, v149
	v_add_f32_e32 v96, v159, v96
	v_exp_f32_e32 v146, v146
	v_add_f32_e32 v96, v102, v96
	v_exp_f32_e32 v147, v147
	v_add_f32_e32 v96, v103, v96
	v_exp_f32_e32 v144, v144
	v_add_f32_e32 v96, v148, v96
	v_exp_f32_e32 v145, v145
	v_add_f32_e32 v96, v149, v96
	v_exp_f32_e32 v150, v142
	v_add_f32_e32 v96, v146, v96
	v_exp_f32_e32 v151, v143
	v_add_f32_e32 v96, v147, v96
	v_exp_f32_e32 v162, v140
	v_add_f32_e32 v96, v144, v96
	v_exp_f32_e32 v163, v141
	v_add_f32_e32 v96, v145, v96
	v_exp_f32_e32 v164, v138
	v_add_f32_e32 v96, v150, v96
	v_exp_f32_e32 v165, v139
	v_add_f32_e32 v96, v151, v96
	v_exp_f32_e32 v166, v136
	v_add_f32_e32 v96, v162, v96
	v_exp_f32_e32 v167, v137
	v_add_f32_e32 v96, v163, v96
	v_add_f32_e32 v96, v164, v96
	v_add_f32_e32 v96, v165, v96
	v_add_f32_e32 v96, v166, v96
	v_add_f32_e32 v96, v167, v96
	v_mov_b32_e32 v97, v96
	s_nop 1
	v_permlane32_swap_b32_e32 v96, v97
	v_cvt_pk_bf16_f32 v98, v204, v206
	v_cvt_pk_bf16_f32 v99, v202, v205
	v_cvt_pk_bf16_f32 v100, v201, v203
	v_cvt_pk_bf16_f32 v101, v199, v200
	v_cvt_pk_bf16_f32 v136, v157, v197
	v_cvt_pk_bf16_f32 v137, v155, v158
	v_cvt_pk_bf16_f32 v138, v154, v198
	v_cvt_pk_bf16_f32 v139, v156, v159
	v_cvt_pk_bf16_f32 v140, v102, v103
	v_cvt_pk_bf16_f32 v141, v148, v149
	v_cvt_pk_bf16_f32 v142, v146, v147
	v_cvt_pk_bf16_f32 v143, v144, v145
	v_cvt_pk_bf16_f32 v144, v150, v151
	v_cvt_pk_bf16_f32 v145, v162, v163
	v_cvt_pk_bf16_f32 v146, v164, v165
	v_cvt_pk_bf16_f32 v147, v166, v167
	s_nop 0
	v_permlane32_swap_b32_e32 v98, v100
	v_permlane32_swap_b32_e32 v99, v101
	v_permlane32_swap_b32_e32 v136, v138
	v_permlane32_swap_b32_e32 v137, v139
	v_permlane32_swap_b32_e32 v140, v142
	v_permlane32_swap_b32_e32 v141, v143
	v_permlane32_swap_b32_e32 v144, v146
	v_permlane32_swap_b32_e32 v145, v147
	ds_read_b64_tr_b16 v[148:149], v180 offset:0
	ds_read_b64_tr_b16 v[150:151], v180 offset:0x800
	ds_read_b64_tr_b16 v[154:155], v180 offset:0x1000
	ds_read_b64_tr_b16 v[156:157], v180 offset:0x1800
	ds_read_b64_tr_b16 v[162:163], v180 offset:0x2000
	ds_read_b64_tr_b16 v[164:165], v180 offset:0x2800
	ds_read_b64_tr_b16 v[184:185], v180 offset:0x3000
	ds_read_b64_tr_b16 v[186:187], v180 offset:0x3800
	s_waitcnt lgkmcnt(0)
; #define RESC(a) do { if (__any((a) < 1.f)) { if (hi == 0) al_l[r32] = (a); asm volatile("s_waitcnt lgkmcnt(0)" ::: "memory");              \
;                      for (int d_ = 0; d_ < 4; ++d_) for (int r = 0; r < 16; ++r) o[d_][r] *= al_l[crow(r, hi)]; } } while (0)
; #define MASKT(P0_, P1_, t) do { const int kb_ = KBASE(t); if (kb_ + KVBLK - 1 > qlo) mask_tile(P0_, P1_, qm - kb_, W); } while (0)
; template <int VB>
; __device__ __forceinline__ void pv_tile(f32x16* o, int vb0, bf16x8 pa0, bf16x8 pa1, bf16x8 pa2, bf16x8 pa3) {
;     ...
;     PV_D0(0); PV_D0(1); PV_D0(2); PV_D0(3);
;     ...
; }
; __device__ __forceinline__ void block(const BlockRef& cur, const BlockRef& nxt, char* lds, Seam& S) {
;     ...
;     pv_tile<0>(o, vb0, pa0, pa1, pa2, pa3);
;     MASKT(pB0, pB1, NT - 1); partialSM(pB0, pB1, m_reg, mnB, alB); __syncthreads(); RESC(alB);
	s_nop 0
	v_mfma_f32_32x32x16_bf16 v[48:63], v[98:101], v[148:151], v[48:63]
	ds_read_b64_tr_b16 v[148:149], v180 offset:0x200
	ds_read_b64_tr_b16 v[150:151], v180 offset:0xa00
	v_mfma_f32_32x32x16_bf16 v[48:63], v[136:139], v[154:157], v[48:63]
	ds_read_b64_tr_b16 v[154:155], v180 offset:0x1200
	ds_read_b64_tr_b16 v[156:157], v180 offset:0x1a00
	v_mfma_f32_32x32x16_bf16 v[48:63], v[140:143], v[162:165], v[48:63]
	ds_read_b64_tr_b16 v[162:163], v180 offset:0x2200
	ds_read_b64_tr_b16 v[164:165], v180 offset:0x2a00
	ds_read_b64_tr_b16 v[188:189], v180 offset:0x3200
	ds_read_b64_tr_b16 v[190:191], v180 offset:0x3a00
	s_waitcnt lgkmcnt(0)
	v_mfma_f32_32x32x16_bf16 v[48:63], v[144:147], v[184:187], v[48:63]
	v_mfma_f32_32x32x16_bf16 v[32:47], v[98:101], v[148:151], v[32:47]
	ds_read_b64_tr_b16 v[148:149], v180 offset:0x400
	ds_read_b64_tr_b16 v[150:151], v180 offset:0xc00
	v_mfma_f32_32x32x16_bf16 v[32:47], v[136:139], v[154:157], v[32:47]
	ds_read_b64_tr_b16 v[154:155], v180 offset:0x1400
	ds_read_b64_tr_b16 v[156:157], v180 offset:0x1c00
	v_mfma_f32_32x32x16_bf16 v[32:47], v[140:143], v[162:165], v[32:47]
	ds_read_b64_tr_b16 v[162:163], v180 offset:0x2400
	ds_read_b64_tr_b16 v[164:165], v180 offset:0x2c00
	ds_read_b64_tr_b16 v[184:185], v180 offset:0x3400
	ds_read_b64_tr_b16 v[186:187], v180 offset:0x3c00
	s_waitcnt lgkmcnt(0)
	v_mfma_f32_32x32x16_bf16 v[32:47], v[144:147], v[188:191], v[32:47]
	v_mfma_f32_32x32x16_bf16 v[16:31], v[98:101], v[148:151], v[16:31]
	ds_read_b64_tr_b16 v[148:149], v180 offset:0x600
	ds_read_b64_tr_b16 v[150:151], v180 offset:0xe00
	v_mfma_f32_32x32x16_bf16 v[16:31], v[136:139], v[154:157], v[16:31]
	ds_read_b64_tr_b16 v[154:155], v180 offset:0x1600
	ds_read_b64_tr_b16 v[156:157], v180 offset:0x1e00
	v_mfma_f32_32x32x16_bf16 v[16:31], v[140:143], v[162:165], v[16:31]
	ds_read_b64_tr_b16 v[162:163], v180 offset:0x2600
	ds_read_b64_tr_b16 v[164:165], v180 offset:0x2e00
	ds_read_b64_tr_b16 v[188:189], v180 offset:0x3600
	ds_read_b64_tr_b16 v[190:191], v180 offset:0x3e00
	s_waitcnt lgkmcnt(0)
	v_mfma_f32_32x32x16_bf16 v[16:31], v[144:147], v[184:187], v[16:31]
	v_mfma_f32_32x32x16_bf16 v[0:15], v[98:101], v[148:151], v[0:15]
	s_add_i32 s7, s7, -1
	s_cmp_gt_i32 s7, s45
	v_mfma_f32_32x32x16_bf16 v[0:15], v[136:139], v[154:157], v[0:15]
	v_mfma_f32_32x32x16_bf16 v[0:15], v[140:143], v[162:165], v[0:15]
	v_mfma_f32_32x32x16_bf16 v[0:15], v[144:147], v[188:191], v[0:15]
	s_cbranch_scc0 .LBB0_1162
	v_subrev_u32_e32 v98, s6, v181
	v_cmp_gt_u32_e32 vcc, 2.0, v98
	v_add_u32_e32 v99, 0xbfffffe0, v98
	s_nop 0
	v_cndmask_b32_e32 v64, v169, v64, vcc
	v_cmp_lt_u32_e32 vcc, s61, v99
	v_add_u32_e32 v99, 0xbfffffff, v98
	s_nop 0
	v_cndmask_b32_e32 v80, v169, v80, vcc
	v_cmp_lt_u32_e32 vcc, s61, v99
	v_add_u32_e32 v99, 0xbfffffdf, v98
	s_nop 0
	v_cndmask_b32_e32 v65, v169, v65, vcc
	v_cmp_lt_u32_e32 vcc, s61, v99
	v_add_u32_e32 v99, 0xbffffffe, v98
	s_nop 0
	v_cndmask_b32_e32 v81, v169, v81, vcc
	v_cmp_lt_u32_e32 vcc, s61, v99
	v_add_u32_e32 v99, 0xbfffffde, v98
	s_nop 0
	v_cndmask_b32_e32 v66, v169, v66, vcc
	v_cmp_lt_u32_e32 vcc, s61, v99
	v_add_u32_e32 v99, 0xbffffffd, v98
	s_nop 0
	v_cndmask_b32_e32 v82, v169, v82, vcc
	v_cmp_lt_u32_e32 vcc, s61, v99
	v_add_u32_e32 v99, 0xbfffffdd, v98
	s_nop 0
	v_cndmask_b32_e32 v67, v169, v67, vcc
	v_cmp_lt_u32_e32 vcc, s61, v99
	v_add_u32_e32 v99, 0xbffffff8, v98
	s_nop 0
	v_cndmask_b32_e32 v83, v169, v83, vcc
	v_cmp_lt_u32_e32 vcc, s61, v99
	v_add_u32_e32 v99, 0xbfffffd8, v98
	s_nop 0
	v_cndmask_b32_e32 v68, v169, v68, vcc
	v_cmp_lt_u32_e32 vcc, s61, v99
	v_add_u32_e32 v99, 0xbffffff7, v98
	s_nop 0
	v_cndmask_b32_e32 v84, v169, v84, vcc
	v_cmp_lt_u32_e32 vcc, s61, v99
	v_add_u32_e32 v99, 0xbfffffd7, v98
	s_nop 0
	v_cndmask_b32_e32 v69, v169, v69, vcc
	v_cmp_lt_u32_e32 vcc, s61, v99
	v_add_u32_e32 v99, 0xbffffff6, v98
	s_nop 0
	v_cndmask_b32_e32 v85, v169, v85, vcc
	v_cmp_lt_u32_e32 vcc, s61, v99
	v_add_u32_e32 v99, 0xbfffffd6, v98
	s_nop 0
	v_cndmask_b32_e32 v70, v169, v70, vcc
	v_cmp_lt_u32_e32 vcc, s61, v99
	v_add_u32_e32 v99, 0xbffffff5, v98
	s_nop 0
	v_cndmask_b32_e32 v86, v169, v86, vcc
	v_cmp_lt_u32_e32 vcc, s61, v99
	v_add_u32_e32 v99, 0xbfffffd5, v98
	s_nop 0
	v_cndmask_b32_e32 v71, v169, v71, vcc
	v_cmp_lt_u32_e32 vcc, s61, v99
	v_add_u32_e32 v99, 0xbffffff0, v98
	s_nop 0
	v_cndmask_b32_e32 v87, v169, v87, vcc
	v_cmp_lt_u32_e32 vcc, s61, v99
	v_add_u32_e32 v99, 0xbfffffd0, v98
	s_nop 0
	v_cndmask_b32_e32 v72, v169, v72, vcc
	v_cmp_lt_u32_e32 vcc, s61, v99
	v_add_u32_e32 v99, 0xbfffffef, v98
	s_nop 0
	v_cndmask_b32_e32 v88, v169, v88, vcc
	v_cmp_lt_u32_e32 vcc, s61, v99
	v_add_u32_e32 v99, 0xbfffffcf, v98
	s_nop 0
	v_cndmask_b32_e32 v73, v169, v73, vcc
	v_cmp_lt_u32_e32 vcc, s61, v99
	v_add_u32_e32 v99, 0xbfffffee, v98
	s_nop 0
	v_cndmask_b32_e32 v89, v169, v89, vcc
	v_cmp_lt_u32_e32 vcc, s61, v99
	v_add_u32_e32 v99, 0xbfffffce, v98
	s_nop 0
	v_cndmask_b32_e32 v74, v169, v74, vcc
	v_cmp_lt_u32_e32 vcc, s61, v99
	v_add_u32_e32 v99, 0xbfffffed, v98
	s_nop 0
	v_cndmask_b32_e32 v90, v169, v90, vcc
	v_cmp_lt_u32_e32 vcc, s61, v99
	v_add_u32_e32 v99, 0xbfffffcd, v98
	s_nop 0
	v_cndmask_b32_e32 v75, v169, v75, vcc
	v_cmp_lt_u32_e32 vcc, s61, v99
	v_add_u32_e32 v99, 0xbfffffe8, v98
	s_nop 0
	v_cndmask_b32_e32 v91, v169, v91, vcc
	v_cmp_lt_u32_e32 vcc, s61, v99
	v_add_u32_e32 v99, 0xbfffffc8, v98
	s_nop 0
	v_cndmask_b32_e32 v76, v169, v76, vcc
	v_cmp_lt_u32_e32 vcc, s61, v99
	v_add_u32_e32 v99, 0xbfffffe7, v98
	s_nop 0
	v_cndmask_b32_e32 v92, v169, v92, vcc
	v_cmp_lt_u32_e32 vcc, s61, v99
	v_add_u32_e32 v99, 0xbfffffc7, v98
	s_nop 0
	v_cndmask_b32_e32 v77, v169, v77, vcc
	v_cmp_lt_u32_e32 vcc, s61, v99
	v_add_u32_e32 v99, 0xbfffffe6, v98
	s_nop 0
	v_cndmask_b32_e32 v93, v169, v93, vcc
	v_cmp_lt_u32_e32 vcc, s61, v99
	v_add_u32_e32 v99, 0xbfffffc6, v98
	s_nop 0
	v_cndmask_b32_e32 v78, v169, v78, vcc
	v_cmp_lt_u32_e32 vcc, s61, v99
	v_add_u32_e32 v99, 0xbfffffe5, v98
	v_add_u32_e32 v98, 0xbfffffc5, v98
	v_cndmask_b32_e32 v94, v169, v94, vcc
	v_cmp_lt_u32_e32 vcc, s61, v99
	s_nop 1
	v_cndmask_b32_e32 v79, v169, v79, vcc
	v_cmp_lt_u32_e32 vcc, s61, v98
	s_nop 1
	v_cndmask_b32_e32 v95, v169, v95, vcc
